# grid-barrier poll loops: s_sleep 1 removed (back-to-back polling) for lower wake latency
# baseline (speedup 1.0000x reference)
.LBB0_195:
	global_load_dword v15, v16, s[6:7] sc1
	s_waitcnt lgkmcnt(0)
	global_load_dword v0, v16, s[8:9] sc1
	global_load_dword v1, v16, s[10:11] sc1
	global_load_dword v2, v16, s[12:13] sc1
	global_load_dword v3, v16, s[14:15] sc1
	global_load_dword v4, v16, s[16:17] sc1
	global_load_dword v5, v16, s[18:19] sc1
	global_load_dword v6, v16, s[24:25] sc1
	global_load_dword v7, v16, s[26:27] sc1
	global_load_dword v8, v16, s[28:29] sc1
	global_load_dword v9, v16, s[30:31] sc1
	global_load_dword v10, v16, s[34:35] sc1
	global_load_dword v11, v16, s[36:37] sc1
	global_load_dword v12, v16, s[38:39] sc1
	global_load_dword v13, v16, s[40:41] sc1
	global_load_dword v14, v16, s[42:43] sc1
	s_mov_b64 s[44:45], -1
	s_mov_b64 s[46:47], -1
	s_waitcnt vmcnt(14)
	v_add_u32_e32 v17, v0, v15
	s_waitcnt vmcnt(13)
	v_add_u32_e32 v17, v17, v1
	s_waitcnt vmcnt(12)
	v_add_u32_e32 v17, v17, v2
	s_waitcnt vmcnt(11)
	v_add_u32_e32 v17, v17, v3
	s_waitcnt vmcnt(10)
	v_add_u32_e32 v17, v17, v4
	s_waitcnt vmcnt(9)
	v_add_u32_e32 v17, v17, v5
	s_waitcnt vmcnt(8)
	v_add_u32_e32 v17, v17, v6
	s_waitcnt vmcnt(7)
	v_add_u32_e32 v17, v17, v7
	s_waitcnt vmcnt(6)
	v_add_u32_e32 v17, v17, v8
	s_waitcnt vmcnt(5)
	v_add_u32_e32 v17, v17, v9
	s_waitcnt vmcnt(4)
	v_add_u32_e32 v17, v17, v10
	s_waitcnt vmcnt(3)
	v_add_u32_e32 v17, v17, v11
	s_waitcnt vmcnt(2)
	v_add_u32_e32 v17, v17, v12
	s_waitcnt vmcnt(1)
	v_add_u32_e32 v17, v17, v13
	s_waitcnt vmcnt(0)
	v_add_u32_e32 v17, v17, v14
	v_cmp_eq_u32_e32 vcc, s50, v17
	s_cbranch_vccnz .LBB0_194
	s_and_b32 s44, s51, 0xff
	s_cmp_eq_u32 s44, 0
	s_mov_b64 s[44:45], -1
	s_mov_b64 s[48:49], -1
	s_nop 0
	s_cbranch_scc0 .LBB0_199
	global_load_dword v17, v16, s[2:3] sc1
	s_waitcnt vmcnt(0)
	v_cmp_eq_u32_e32 vcc, 0, v17
	s_cbranch_vccnz .LBB0_201
	s_mov_b64 s[48:49], 0

.LBB0_213:
	s_and_b32 s24, s28, 0xff
	s_mov_b64 s[18:19], -1
	s_cmp_lg_u32 s24, 0
	s_mov_b64 s[26:27], -1
	s_nop 0
	s_cbranch_scc1 .LBB0_216
	global_load_dword v2, v0, s[10:11] sc1
	s_waitcnt vmcnt(0)
	v_cmp_eq_u32_e32 vcc, 0, v2
	s_cbranch_vccnz .LBB0_218
	s_mov_b64 s[26:27], 0
	s_mov_b64 s[24:25], -1

.LBB0_230:
	s_and_b32 s18, s28, 0xff
	s_cmp_lg_u32 s18, 0
	s_mov_b64 s[24:25], -1
	s_nop 0
	s_cbranch_scc1 .LBB0_233
	global_load_dword v1, v0, s[10:11] sc1
	s_waitcnt vmcnt(0)
	v_cmp_eq_u32_e32 vcc, 0, v1
	s_cbranch_vccnz .LBB0_235
	s_mov_b64 s[24:25], 0
	s_mov_b64 s[18:19], -1

.LBB0_487:
	global_load_dword v15, v16, s[6:7] sc1
	s_waitcnt lgkmcnt(0)
	global_load_dword v0, v16, s[8:9] sc1
	global_load_dword v1, v16, s[10:11] sc1
	global_load_dword v2, v16, s[12:13] sc1
	global_load_dword v3, v16, s[14:15] sc1
	global_load_dword v4, v16, s[16:17] sc1
	global_load_dword v5, v16, s[18:19] sc1
	global_load_dword v6, v16, s[24:25] sc1
	global_load_dword v7, v16, s[26:27] sc1
	global_load_dword v8, v16, s[28:29] sc1
	global_load_dword v9, v16, s[30:31] sc1
	global_load_dword v10, v16, s[34:35] sc1
	global_load_dword v11, v16, s[36:37] sc1
	global_load_dword v12, v16, s[38:39] sc1
	global_load_dword v13, v16, s[40:41] sc1
	global_load_dword v14, v16, s[42:43] sc1
	s_mov_b64 s[44:45], -1
	s_mov_b64 s[46:47], -1
	s_waitcnt vmcnt(14)
	v_add_u32_e32 v17, v0, v15
	s_waitcnt vmcnt(13)
	v_add_u32_e32 v17, v17, v1
	s_waitcnt vmcnt(12)
	v_add_u32_e32 v17, v17, v2
	s_waitcnt vmcnt(11)
	v_add_u32_e32 v17, v17, v3
	s_waitcnt vmcnt(10)
	v_add_u32_e32 v17, v17, v4
	s_waitcnt vmcnt(9)
	v_add_u32_e32 v17, v17, v5
	s_waitcnt vmcnt(8)
	v_add_u32_e32 v17, v17, v6
	s_waitcnt vmcnt(7)
	v_add_u32_e32 v17, v17, v7
	s_waitcnt vmcnt(6)
	v_add_u32_e32 v17, v17, v8
	s_waitcnt vmcnt(5)
	v_add_u32_e32 v17, v17, v9
	s_waitcnt vmcnt(4)
	v_add_u32_e32 v17, v17, v10
	s_waitcnt vmcnt(3)
	v_add_u32_e32 v17, v17, v11
	s_waitcnt vmcnt(2)
	v_add_u32_e32 v17, v17, v12
	s_waitcnt vmcnt(1)
	v_add_u32_e32 v17, v17, v13
	s_waitcnt vmcnt(0)
	v_add_u32_e32 v17, v17, v14
	v_cmp_eq_u32_e32 vcc, s50, v17
	s_cbranch_vccnz .LBB0_486
	s_and_b32 s44, s51, 0xff
	s_cmp_eq_u32 s44, 0
	s_mov_b64 s[44:45], -1
	s_mov_b64 s[48:49], -1
	s_nop 0
	s_cbranch_scc0 .LBB0_491
	global_load_dword v17, v16, s[4:5] sc1
	s_waitcnt vmcnt(0)
	v_cmp_eq_u32_e32 vcc, 0, v17
	s_cbranch_vccnz .LBB0_493
	s_mov_b64 s[48:49], 0

.LBB0_668:
	global_load_dword v15, v16, s[8:9] sc1
	s_waitcnt lgkmcnt(0)
	global_load_dword v0, v16, s[10:11] sc1
	global_load_dword v1, v16, s[12:13] sc1
	global_load_dword v2, v16, s[14:15] sc1
	global_load_dword v3, v16, s[16:17] sc1
	global_load_dword v4, v16, s[18:19] sc1
	global_load_dword v5, v16, s[24:25] sc1
	global_load_dword v6, v16, s[26:27] sc1
	global_load_dword v7, v16, s[28:29] sc1
	global_load_dword v8, v16, s[30:31] sc1
	global_load_dword v9, v16, s[34:35] sc1
	global_load_dword v10, v16, s[36:37] sc1
	global_load_dword v11, v16, s[38:39] sc1
	global_load_dword v12, v16, s[40:41] sc1
	global_load_dword v13, v16, s[42:43] sc1
	global_load_dword v14, v16, s[44:45] sc1
	s_mov_b64 s[46:47], -1
	s_mov_b64 s[48:49], -1
	s_waitcnt vmcnt(14)
	v_add_u32_e32 v17, v0, v15
	s_waitcnt vmcnt(13)
	v_add_u32_e32 v17, v17, v1
	s_waitcnt vmcnt(12)
	v_add_u32_e32 v17, v17, v2
	s_waitcnt vmcnt(11)
	v_add_u32_e32 v17, v17, v3
	s_waitcnt vmcnt(10)
	v_add_u32_e32 v17, v17, v4
	s_waitcnt vmcnt(9)
	v_add_u32_e32 v17, v17, v5
	s_waitcnt vmcnt(8)
	v_add_u32_e32 v17, v17, v6
	s_waitcnt vmcnt(7)
	v_add_u32_e32 v17, v17, v7
	s_waitcnt vmcnt(6)
	v_add_u32_e32 v17, v17, v8
	s_waitcnt vmcnt(5)
	v_add_u32_e32 v17, v17, v9
	s_waitcnt vmcnt(4)
	v_add_u32_e32 v17, v17, v10
	s_waitcnt vmcnt(3)
	v_add_u32_e32 v17, v17, v11
	s_waitcnt vmcnt(2)
	v_add_u32_e32 v17, v17, v12
	s_waitcnt vmcnt(1)
	v_add_u32_e32 v17, v17, v13
	s_waitcnt vmcnt(0)
	v_add_u32_e32 v17, v17, v14
	v_cmp_eq_u32_e32 vcc, s52, v17
	s_cbranch_vccnz .LBB0_667
	s_and_b32 s46, s53, 0xff
	s_cmp_eq_u32 s46, 0
	s_mov_b64 s[46:47], -1
	s_mov_b64 s[50:51], -1
	s_nop 0
	s_cbranch_scc0 .LBB0_672
	global_load_dword v17, v16, s[6:7] sc1
	s_waitcnt vmcnt(0)
	v_cmp_eq_u32_e32 vcc, 0, v17
	s_cbranch_vccnz .LBB0_674
	s_mov_b64 s[50:51], 0

.LBB0_686:
	s_and_b32 s26, s30, 0xff
	s_mov_b64 s[24:25], -1
	s_cmp_lg_u32 s26, 0
	s_mov_b64 s[28:29], -1
	s_nop 0
	s_cbranch_scc1 .LBB0_689
	global_load_dword v2, v0, s[12:13] sc1
	s_waitcnt vmcnt(0)
	v_cmp_eq_u32_e32 vcc, 0, v2
	s_cbranch_vccnz .LBB0_691
	s_mov_b64 s[28:29], 0
	s_mov_b64 s[26:27], -1

.LBB0_703:
	s_and_b32 s24, s30, 0xff
	s_cmp_lg_u32 s24, 0
	s_mov_b64 s[26:27], -1
	s_nop 0
	s_cbranch_scc1 .LBB0_706
	global_load_dword v1, v0, s[12:13] sc1
	s_waitcnt vmcnt(0)
	v_cmp_eq_u32_e32 vcc, 0, v1
	s_cbranch_vccnz .LBB0_708
	s_mov_b64 s[26:27], 0
	s_mov_b64 s[24:25], -1
